# no setprio plus the five K-loop heads aligned to 64 bytes
# speedup vs baseline: 1.0061x; 1.0061x over previous
.Lnb_p1:
	s_add_i32 s7, s4, 0xfff84000
	s_cmp_eq_u32 s6, 28
	s_cselect_b32 s17, s0, s7
	s_cselect_b32 s16, s1, s5
	s_or_b32 s7, s17, 0x4000
	s_mov_b32 m0, s79
	s_nop 0
	buffer_load_dwordx4 v242, s[24:27], s4 offen lds
	s_nop 0
	s_mov_b32 m0, s83
	s_nop 0
	buffer_load_dwordx4 v243, s[24:27], s4 offen lds
	s_waitcnt vmcnt(24)
	s_waitcnt lgkmcnt(0)
	s_barrier
	s_waitcnt lgkmcnt(7)
	v_mfma_f32_16x16x32_bf16 v[180:183], v[16:19], v[192:195], 0
	v_mfma_f32_16x16x32_bf16 v[164:167], v[24:27], v[192:195], 0
	s_waitcnt lgkmcnt(5)
	v_mfma_f32_16x16x32_bf16 v[148:151], v[16:19], v[200:203], 0
	v_mfma_f32_16x16x32_bf16 v[140:143], v[24:27], v[200:203], 0
	s_waitcnt lgkmcnt(3)
	v_mfma_f32_16x16x32_bf16 v[132:135], v[16:19], v[220:223], 0
	v_mfma_f32_16x16x32_bf16 v[124:127], v[24:27], v[220:223], 0
	s_waitcnt lgkmcnt(1)
	v_mfma_f32_16x16x32_bf16 v[116:119], v[16:19], v[228:231], 0
	v_mfma_f32_16x16x32_bf16 v[108:111], v[24:27], v[228:231], 0
	v_mfma_f32_16x16x32_bf16 v[180:183], v[20:23], v[196:199], v[180:183]
	v_mfma_f32_16x16x32_bf16 v[164:167], v[28:31], v[196:199], v[164:167]
	v_mfma_f32_16x16x32_bf16 v[148:151], v[20:23], v[204:207], v[148:151]
	v_mfma_f32_16x16x32_bf16 v[140:143], v[28:31], v[204:207], v[140:143]
	v_mfma_f32_16x16x32_bf16 v[132:135], v[20:23], v[224:227], v[132:135]
	v_mfma_f32_16x16x32_bf16 v[124:127], v[28:31], v[224:227], v[124:127]
	s_waitcnt lgkmcnt(0)
	v_mfma_f32_16x16x32_bf16 v[116:119], v[20:23], v[246:249], v[116:119]
	v_mfma_f32_16x16x32_bf16 v[108:111], v[28:31], v[246:249], v[108:111]
	v_mfma_f32_16x16x32_bf16 v[172:175], v[152:155], v[192:195], 0
	v_mfma_f32_16x16x32_bf16 v[156:159], v[168:171], v[192:195], 0
	v_mfma_f32_16x16x32_bf16 v[144:147], v[152:155], v[200:203], 0
	v_mfma_f32_16x16x32_bf16 v[136:139], v[168:171], v[200:203], 0
	v_mfma_f32_16x16x32_bf16 v[128:131], v[152:155], v[220:223], 0
	v_mfma_f32_16x16x32_bf16 v[120:123], v[168:171], v[220:223], 0
	v_mfma_f32_16x16x32_bf16 v[112:115], v[152:155], v[228:231], 0
	v_mfma_f32_16x16x32_bf16 v[104:107], v[168:171], v[228:231], 0
	v_mfma_f32_16x16x32_bf16 v[172:175], v[160:163], v[196:199], v[172:175]
	v_mfma_f32_16x16x32_bf16 v[156:159], v[176:179], v[196:199], v[156:159]
	v_mfma_f32_16x16x32_bf16 v[144:147], v[160:163], v[204:207], v[144:147]
	v_mfma_f32_16x16x32_bf16 v[136:139], v[176:179], v[204:207], v[136:139]
	v_mfma_f32_16x16x32_bf16 v[128:131], v[160:163], v[224:227], v[128:131]
	v_mfma_f32_16x16x32_bf16 v[120:123], v[176:179], v[224:227], v[120:123]
	v_mfma_f32_16x16x32_bf16 v[112:115], v[160:163], v[246:249], v[112:115]
	v_mfma_f32_16x16x32_bf16 v[104:107], v[176:179], v[246:249], v[104:107]
	s_barrier
	ds_read_b128 v[192:195], v245 offset:16384
	ds_read_b128 v[196:199], v245 offset:17408
	ds_read_b128 v[200:203], v245 offset:18432
	ds_read_b128 v[204:207], v245 offset:19456
	ds_read_b128 v[220:223], v245 offset:20480
	ds_read_b128 v[224:227], v245 offset:21504
	ds_read_b128 v[228:231], v245 offset:22528
	ds_read_b128 v[246:249], v245 offset:23552
	s_mov_b32 m0, s51
	s_nop 0
	buffer_load_dwordx4 v242, s[56:59], s16 offen lds
	s_add_i32 s18, s16, 0x80000
	s_mov_b32 m0, s52
	s_nop 0
	buffer_load_dwordx4 v243, s[56:59], s16 offen lds
	s_nop 0
	s_mov_b32 m0, s53
	s_nop 0
	buffer_load_dwordx4 v242, s[56:59], s18 offen lds
	s_nop 0
	s_mov_b32 m0, s55
	s_nop 0
	buffer_load_dwordx4 v243, s[56:59], s18 offen lds
	s_nop 0
	s_mov_b32 m0, s31
	s_nop 0
	buffer_load_dwordx4 v242, s[24:27], s17 offen lds
	s_nop 0
	s_mov_b32 m0, s68
	s_nop 0
	buffer_load_dwordx4 v243, s[24:27], s17 offen lds
	s_waitcnt vmcnt(24)
	s_waitcnt lgkmcnt(0)
	s_barrier
	s_waitcnt lgkmcnt(7)
	v_mfma_f32_16x16x32_bf16 v[76:79], v[16:19], v[192:195], 0
	v_mfma_f32_16x16x32_bf16 v[68:71], v[24:27], v[192:195], 0
	s_waitcnt lgkmcnt(5)
	v_mfma_f32_16x16x32_bf16 v[60:63], v[16:19], v[200:203], 0
	v_mfma_f32_16x16x32_bf16 v[52:55], v[24:27], v[200:203], 0
	s_waitcnt lgkmcnt(3)
	v_mfma_f32_16x16x32_bf16 v[44:47], v[16:19], v[220:223], 0
	v_mfma_f32_16x16x32_bf16 v[36:39], v[24:27], v[220:223], 0
	s_waitcnt lgkmcnt(1)
	v_mfma_f32_16x16x32_bf16 v[12:15], v[16:19], v[228:231], 0
	v_mfma_f32_16x16x32_bf16 v[4:7], v[24:27], v[228:231], 0
	v_mfma_f32_16x16x32_bf16 v[76:79], v[20:23], v[196:199], v[76:79]
	v_mfma_f32_16x16x32_bf16 v[68:71], v[28:31], v[196:199], v[68:71]
	v_mfma_f32_16x16x32_bf16 v[60:63], v[20:23], v[204:207], v[60:63]
	v_mfma_f32_16x16x32_bf16 v[52:55], v[28:31], v[204:207], v[52:55]
	v_mfma_f32_16x16x32_bf16 v[44:47], v[20:23], v[224:227], v[44:47]
	v_mfma_f32_16x16x32_bf16 v[36:39], v[28:31], v[224:227], v[36:39]
	s_waitcnt lgkmcnt(0)
	v_mfma_f32_16x16x32_bf16 v[12:15], v[20:23], v[246:249], v[12:15]
	v_mfma_f32_16x16x32_bf16 v[4:7], v[28:31], v[246:249], v[4:7]
	v_mfma_f32_16x16x32_bf16 v[40:43], v[152:155], v[220:223], 0
	v_mfma_f32_16x16x32_bf16 v[32:35], v[168:171], v[220:223], 0
	v_mfma_f32_16x16x32_bf16 v[8:11], v[152:155], v[228:231], 0
	v_mfma_f32_16x16x32_bf16 v[0:3], v[168:171], v[228:231], 0
	v_mfma_f32_16x16x32_bf16 v[16:19], v[152:155], v[192:195], 0
	v_mfma_f32_16x16x32_bf16 v[20:23], v[168:171], v[192:195], 0
	v_mfma_f32_16x16x32_bf16 v[24:27], v[152:155], v[200:203], 0
	v_mfma_f32_16x16x32_bf16 v[28:31], v[168:171], v[200:203], 0
	v_mfma_f32_16x16x32_bf16 v[40:43], v[160:163], v[224:227], v[40:43]
	v_mfma_f32_16x16x32_bf16 v[32:35], v[176:179], v[224:227], v[32:35]
	v_mfma_f32_16x16x32_bf16 v[8:11], v[160:163], v[246:249], v[8:11]
	v_mfma_f32_16x16x32_bf16 v[0:3], v[176:179], v[246:249], v[0:3]
	v_mfma_f32_16x16x32_bf16 v[16:19], v[160:163], v[196:199], v[16:19]
	v_mfma_f32_16x16x32_bf16 v[20:23], v[176:179], v[196:199], v[20:23]
	v_mfma_f32_16x16x32_bf16 v[24:27], v[160:163], v[204:207], v[24:27]
	v_mfma_f32_16x16x32_bf16 v[28:31], v[176:179], v[204:207], v[28:31]
	s_barrier
	v_add_u32_e32 v72, 0x18000, v83
	v_add_u32_e32 v80, 0x1c000, v83
	ds_read_b128 v[48:51], v72
	ds_read_b128 v[56:59], v72 offset:1024
	ds_read_b128 v[64:67], v72 offset:2048
	ds_read_b128 v[72:75], v72 offset:3072
	ds_read_b128 v[152:155], v80
	ds_read_b128 v[160:163], v80 offset:1024
	ds_read_b128 v[168:171], v80 offset:2048
	ds_read_b128 v[176:179], v80 offset:3072
	ds_read_b128 v[192:195], v245 offset:32768
	ds_read_b128 v[196:199], v245 offset:33792
	ds_read_b128 v[200:203], v245 offset:34816
	ds_read_b128 v[204:207], v245 offset:35840
	ds_read_b128 v[220:223], v245 offset:36864
	ds_read_b128 v[224:227], v245 offset:37888
	ds_read_b128 v[228:231], v245 offset:38912
	ds_read_b128 v[246:249], v245 offset:39936
	s_add_i32 s17, s17, 0x80000
	s_mov_b32 m0, s69
	s_nop 0
	buffer_load_dwordx4 v242, s[24:27], s17 offen lds
	s_nop 0
	s_mov_b32 m0, s70
	s_nop 0
	buffer_load_dwordx4 v243, s[24:27], s17 offen lds
	s_waitcnt vmcnt(8)
	s_waitcnt lgkmcnt(0)
	s_barrier
	s_waitcnt lgkmcnt(7)
	v_mfma_f32_16x16x32_bf16 v[180:183], v[48:51], v[192:195], v[180:183]
	v_mfma_f32_16x16x32_bf16 v[164:167], v[64:67], v[192:195], v[164:167]
	s_waitcnt lgkmcnt(5)
	v_mfma_f32_16x16x32_bf16 v[148:151], v[48:51], v[200:203], v[148:151]
	v_mfma_f32_16x16x32_bf16 v[140:143], v[64:67], v[200:203], v[140:143]
	s_waitcnt lgkmcnt(3)
	v_mfma_f32_16x16x32_bf16 v[132:135], v[48:51], v[220:223], v[132:135]
	v_mfma_f32_16x16x32_bf16 v[124:127], v[64:67], v[220:223], v[124:127]
	s_waitcnt lgkmcnt(1)
	v_mfma_f32_16x16x32_bf16 v[116:119], v[48:51], v[228:231], v[116:119]
	v_mfma_f32_16x16x32_bf16 v[108:111], v[64:67], v[228:231], v[108:111]
	v_mfma_f32_16x16x32_bf16 v[180:183], v[56:59], v[196:199], v[180:183]
	v_mfma_f32_16x16x32_bf16 v[164:167], v[72:75], v[196:199], v[164:167]
	v_mfma_f32_16x16x32_bf16 v[148:151], v[56:59], v[204:207], v[148:151]
	v_mfma_f32_16x16x32_bf16 v[140:143], v[72:75], v[204:207], v[140:143]
	v_mfma_f32_16x16x32_bf16 v[132:135], v[56:59], v[224:227], v[132:135]
	v_mfma_f32_16x16x32_bf16 v[124:127], v[72:75], v[224:227], v[124:127]
	s_waitcnt lgkmcnt(0)
	v_mfma_f32_16x16x32_bf16 v[116:119], v[56:59], v[246:249], v[116:119]
	v_mfma_f32_16x16x32_bf16 v[108:111], v[72:75], v[246:249], v[108:111]
	v_mfma_f32_16x16x32_bf16 v[172:175], v[152:155], v[192:195], v[172:175]
	v_mfma_f32_16x16x32_bf16 v[156:159], v[168:171], v[192:195], v[156:159]
	v_mfma_f32_16x16x32_bf16 v[144:147], v[152:155], v[200:203], v[144:147]
	v_mfma_f32_16x16x32_bf16 v[136:139], v[168:171], v[200:203], v[136:139]
	v_mfma_f32_16x16x32_bf16 v[128:131], v[152:155], v[220:223], v[128:131]
	v_mfma_f32_16x16x32_bf16 v[120:123], v[168:171], v[220:223], v[120:123]
	v_mfma_f32_16x16x32_bf16 v[112:115], v[152:155], v[228:231], v[112:115]
	v_mfma_f32_16x16x32_bf16 v[104:107], v[168:171], v[228:231], v[104:107]
	v_mfma_f32_16x16x32_bf16 v[172:175], v[160:163], v[196:199], v[172:175]
	v_mfma_f32_16x16x32_bf16 v[156:159], v[176:179], v[196:199], v[156:159]
	v_mfma_f32_16x16x32_bf16 v[144:147], v[160:163], v[204:207], v[144:147]
	v_mfma_f32_16x16x32_bf16 v[136:139], v[176:179], v[204:207], v[136:139]
	v_mfma_f32_16x16x32_bf16 v[128:131], v[160:163], v[224:227], v[128:131]
	v_mfma_f32_16x16x32_bf16 v[120:123], v[176:179], v[224:227], v[120:123]
	v_mfma_f32_16x16x32_bf16 v[112:115], v[160:163], v[246:249], v[112:115]
	v_mfma_f32_16x16x32_bf16 v[104:107], v[176:179], v[246:249], v[104:107]
	s_barrier
	ds_read_b128 v[192:195], v245 offset:49152
	ds_read_b128 v[196:199], v245 offset:50176
	ds_read_b128 v[200:203], v245 offset:51200
	ds_read_b128 v[204:207], v245 offset:52224
	ds_read_b128 v[220:223], v245 offset:53248
	ds_read_b128 v[224:227], v245 offset:54272
	ds_read_b128 v[228:231], v245 offset:55296
	ds_read_b128 v[246:249], v245 offset:56320
	s_or_b32 s17, s16, 0x4000
	s_mov_b32 m0, s73
	s_nop 0
	buffer_load_dwordx4 v242, s[56:59], s17 offen lds
	s_add_i32 s16, s16, 0x84000
	s_mov_b32 m0, s74
	s_nop 0
	buffer_load_dwordx4 v243, s[56:59], s17 offen lds
	s_nop 0
	s_mov_b32 m0, s77
	s_nop 0
	buffer_load_dwordx4 v242, s[56:59], s16 offen lds
	s_nop 0
	s_mov_b32 m0, s78
	s_nop 0
	buffer_load_dwordx4 v243, s[56:59], s16 offen lds
	s_nop 0
	s_mov_b32 m0, s75
	s_nop 0
	buffer_load_dwordx4 v242, s[24:27], s7 offen lds
	s_nop 0
	s_mov_b32 m0, s76
	s_nop 0
	buffer_load_dwordx4 v243, s[24:27], s7 offen lds
	s_waitcnt vmcnt(8)
	s_waitcnt lgkmcnt(0)
	s_barrier
	s_waitcnt lgkmcnt(7)
	v_mfma_f32_16x16x32_bf16 v[76:79], v[48:51], v[192:195], v[76:79]
	v_mfma_f32_16x16x32_bf16 v[68:71], v[64:67], v[192:195], v[68:71]
	s_waitcnt lgkmcnt(5)
	v_mfma_f32_16x16x32_bf16 v[60:63], v[48:51], v[200:203], v[60:63]
	v_mfma_f32_16x16x32_bf16 v[52:55], v[64:67], v[200:203], v[52:55]
	s_waitcnt lgkmcnt(3)
	v_mfma_f32_16x16x32_bf16 v[44:47], v[48:51], v[220:223], v[44:47]
	v_mfma_f32_16x16x32_bf16 v[36:39], v[64:67], v[220:223], v[36:39]
	s_waitcnt lgkmcnt(1)
	v_mfma_f32_16x16x32_bf16 v[12:15], v[48:51], v[228:231], v[12:15]
	v_mfma_f32_16x16x32_bf16 v[4:7], v[64:67], v[228:231], v[4:7]
	v_mfma_f32_16x16x32_bf16 v[76:79], v[56:59], v[196:199], v[76:79]
	v_mfma_f32_16x16x32_bf16 v[68:71], v[72:75], v[196:199], v[68:71]
	v_mfma_f32_16x16x32_bf16 v[60:63], v[56:59], v[204:207], v[60:63]
	v_mfma_f32_16x16x32_bf16 v[52:55], v[72:75], v[204:207], v[52:55]
	v_mfma_f32_16x16x32_bf16 v[44:47], v[56:59], v[224:227], v[44:47]
	v_mfma_f32_16x16x32_bf16 v[36:39], v[72:75], v[224:227], v[36:39]
	s_waitcnt lgkmcnt(0)
	v_mfma_f32_16x16x32_bf16 v[12:15], v[56:59], v[246:249], v[12:15]
	v_mfma_f32_16x16x32_bf16 v[4:7], v[72:75], v[246:249], v[4:7]
	v_mfma_f32_16x16x32_bf16 v[16:19], v[152:155], v[192:195], v[16:19]
	v_mfma_f32_16x16x32_bf16 v[72:75], v[160:163], v[196:199], v[16:19]
	v_mfma_f32_16x16x32_bf16 v[16:19], v[168:171], v[192:195], v[20:23]
	v_mfma_f32_16x16x32_bf16 v[64:67], v[176:179], v[196:199], v[16:19]
	v_mfma_f32_16x16x32_bf16 v[16:19], v[152:155], v[200:203], v[24:27]
	v_mfma_f32_16x16x32_bf16 v[56:59], v[160:163], v[204:207], v[16:19]
	v_mfma_f32_16x16x32_bf16 v[16:19], v[168:171], v[200:203], v[28:31]
	v_mfma_f32_16x16x32_bf16 v[48:51], v[176:179], v[204:207], v[16:19]
	v_mfma_f32_16x16x32_bf16 v[16:19], v[152:155], v[220:223], v[40:43]
	v_mfma_f32_16x16x32_bf16 v[40:43], v[160:163], v[224:227], v[16:19]
	v_mfma_f32_16x16x32_bf16 v[16:19], v[168:171], v[220:223], v[32:35]
	v_mfma_f32_16x16x32_bf16 v[8:11], v[152:155], v[228:231], v[8:11]
	v_mfma_f32_16x16x32_bf16 v[0:3], v[168:171], v[228:231], v[0:3]
	v_mfma_f32_16x16x32_bf16 v[32:35], v[176:179], v[224:227], v[16:19]
	v_mfma_f32_16x16x32_bf16 v[8:11], v[160:163], v[246:249], v[8:11]
	v_mfma_f32_16x16x32_bf16 v[0:3], v[176:179], v[246:249], v[0:3]
	s_barrier
	s_add_i32 s6, s6, 2
	s_add_i32 s4, s4, 0x8000
	s_add_i32 s5, s5, 0x8000
	.p2align	6

.LBB0_593:
	v_writelane_b32 v254, s3, 27
	s_lshl_b32 s1, s3, 20
	v_writelane_b32 v254, s1, 29
	s_and_b64 s[2:3], s[10:11], exec
	v_writelane_b32 v254, s6, 25
	s_cselect_b32 vcc_lo, s1, s96
	s_lshl_b32 s1, s6, 20
	v_writelane_b32 v254, s10, 23
	s_and_b64 s[2:3], s[10:11], exec
	s_cselect_b32 vcc_hi, s1, s38
	v_writelane_b32 v254, s11, 24
	v_writelane_b32 v254, s1, 31
	s_lshl_b32 s1, s0, 20
	s_lshl_b32 s0, s92, 17
	s_add_i32 s91, s1, s0
	v_writelane_b32 v254, s1, 33
	s_or_b32 s90, s91, 0x10000
	s_or_b32 s88, s91, 0x2000
	s_or_b32 s81, s91, 0x12000
	s_or_b32 s80, s91, 0x4000
	s_or_b32 s89, s91, 0x14000
	s_or_b32 s33, s91, 0x6000
	s_or_b32 s3, s91, 0x16000
	s_or_b32 s2, s91, 0x8000
	s_or_b32 s1, s91, 0x18000
	s_or_b32 s0, s91, 0xa000
	s_or_b32 s37, s91, 0x1a000
	s_or_b32 s52, s91, 0xc000
	s_or_b32 s56, s91, 0x1c000
	s_or_b32 s39, s91, 0xe000
	s_or_b32 s36, s91, 0x1e000
	v_readlane_b32 s70, v251, 1
	v_readlane_b32 s71, v251, 2
	s_add_u32 s4, s70, s91
	s_addc_u32 s5, s71, 0
	s_add_u32 s6, s70, s90
	s_addc_u32 s7, s71, 0
	s_add_u32 s8, s70, s88
	s_addc_u32 s9, s71, 0
	s_add_u32 s10, s70, s81
	s_addc_u32 s11, s71, 0
	s_add_u32 s12, s70, s80
	s_addc_u32 s13, s71, 0
	s_add_u32 s14, s70, s89
	s_addc_u32 s15, s71, 0
	s_add_u32 s16, s70, s33
	s_addc_u32 s17, s71, 0
	s_add_u32 s18, s70, s3
	s_addc_u32 s19, s71, 0
	s_add_u32 s28, s70, s2
	s_addc_u32 s29, s71, 0
	s_add_u32 s40, s70, s1
	s_addc_u32 s41, s71, 0
	s_add_u32 s42, s70, s0
	s_addc_u32 s43, s71, 0
	s_add_u32 s44, s70, s37
	s_addc_u32 s45, s71, 0
	v_writelane_b32 v254, s52, 41
	s_add_u32 s52, s70, s52
	s_addc_u32 s53, s71, 0
	v_writelane_b32 v254, s56, 39
	s_add_u32 s56, s70, s56
	s_addc_u32 s57, s71, 0
	s_add_u32 s68, s70, s39
	s_addc_u32 s69, s71, 0
	v_mov_b32_e32 v80, v81
	v_mov_b32_e32 v82, v81
	v_mov_b32_e32 v83, v81
	v_writelane_b32 v254, s39, 37
	s_add_u32 s70, s70, s36
	v_mov_b64_e32 v[0:1], v[80:81]
	v_mov_b64_e32 v[4:5], v[80:81]
	v_mov_b64_e32 v[16:17], v[80:81]
	v_mov_b64_e32 v[20:21], v[80:81]
	v_mov_b64_e32 v[32:33], v[80:81]
	v_mov_b64_e32 v[36:37], v[80:81]
	s_waitcnt vmcnt(5)
	v_mov_b64_e32 v[48:49], v[80:81]
	s_waitcnt vmcnt(4)
	v_mov_b64_e32 v[52:53], v[80:81]
	v_mov_b64_e32 v[8:9], v[80:81]
	v_mov_b64_e32 v[12:13], v[80:81]
	v_mov_b64_e32 v[24:25], v[80:81]
	v_mov_b64_e32 v[28:29], v[80:81]
	v_mov_b64_e32 v[40:41], v[80:81]
	v_mov_b64_e32 v[44:45], v[80:81]
	s_waitcnt vmcnt(3)
	v_mov_b64_e32 v[56:57], v[80:81]
	s_waitcnt vmcnt(2)
	v_mov_b64_e32 v[60:61], v[80:81]
	v_mov_b64_e32 v[64:65], v[80:81]
	v_mov_b64_e32 v[68:69], v[80:81]
	v_mov_b64_e32 v[106:107], v[82:83]
	v_mov_b64_e32 v[110:111], v[82:83]
	v_mov_b64_e32 v[122:123], v[82:83]
	v_mov_b64_e32 v[126:127], v[82:83]
	v_mov_b64_e32 v[138:139], v[82:83]
	v_mov_b64_e32 v[142:143], v[82:83]
	v_mov_b64_e32 v[72:73], v[80:81]
	v_mov_b64_e32 v[76:77], v[80:81]
	v_mov_b64_e32 v[114:115], v[82:83]
	v_mov_b64_e32 v[118:119], v[82:83]
	v_mov_b64_e32 v[130:131], v[82:83]
	v_mov_b64_e32 v[134:135], v[82:83]
	v_mov_b64_e32 v[146:147], v[82:83]
	v_mov_b64_e32 v[150:151], v[82:83]
	v_writelane_b32 v254, s36, 35
	s_addc_u32 s71, s71, 0
	s_add_i32 s93, s38, 0x8000
	s_mov_b32 s38, -2
	s_mov_b32 s39, 0
	v_mov_b64_e32 v[2:3], v[82:83]
	v_mov_b64_e32 v[6:7], v[82:83]
	v_mov_b64_e32 v[18:19], v[82:83]
	v_mov_b64_e32 v[22:23], v[82:83]
	v_mov_b64_e32 v[34:35], v[82:83]
	v_mov_b64_e32 v[38:39], v[82:83]
	v_mov_b64_e32 v[50:51], v[82:83]
	v_mov_b64_e32 v[54:55], v[82:83]
	v_mov_b64_e32 v[10:11], v[82:83]
	v_mov_b64_e32 v[14:15], v[82:83]
	v_mov_b64_e32 v[26:27], v[82:83]
	v_mov_b64_e32 v[30:31], v[82:83]
	v_mov_b64_e32 v[42:43], v[82:83]
	v_mov_b64_e32 v[46:47], v[82:83]
	v_mov_b64_e32 v[58:59], v[82:83]
	v_mov_b64_e32 v[62:63], v[82:83]
	v_mov_b64_e32 v[66:67], v[82:83]
	v_mov_b64_e32 v[70:71], v[82:83]
	v_mov_b64_e32 v[104:105], v[80:81]
	v_mov_b64_e32 v[108:109], v[80:81]
	v_mov_b64_e32 v[120:121], v[80:81]
	v_mov_b64_e32 v[124:125], v[80:81]
	v_mov_b64_e32 v[136:137], v[80:81]
	v_mov_b64_e32 v[140:141], v[80:81]
	v_mov_b64_e32 v[74:75], v[82:83]
	v_mov_b64_e32 v[78:79], v[82:83]
	v_mov_b64_e32 v[112:113], v[80:81]
	v_mov_b64_e32 v[116:117], v[80:81]
	v_mov_b64_e32 v[128:129], v[80:81]
	v_mov_b64_e32 v[132:133], v[80:81]
	v_mov_b64_e32 v[144:145], v[80:81]
	v_mov_b64_e32 v[148:149], v[80:81]
	s_branch .LBB0_595
	.p2align	6

.Lnb_p4:
	s_add_i32 s11, s8, 0xfff84000
	s_cmp_eq_u32 s10, 28
	s_cselect_b32 s13, s6, s11
	s_cselect_b32 s12, s7, s9
	s_or_b32 s11, s13, 0x4000
	s_mov_b32 m0, s89
	s_nop 0
	buffer_load_dwordx4 v220, s[64:67], s8 offen lds
	s_nop 0
	s_mov_b32 m0, s91
	s_nop 0
	buffer_load_dwordx4 v221, s[64:67], s8 offen lds
	s_waitcnt vmcnt(24)
	s_waitcnt lgkmcnt(0)
	s_barrier
	s_waitcnt lgkmcnt(7)
	v_mfma_f32_16x16x32_bf16 v[164:167], v[128:131], v[184:187], 0
	v_mfma_f32_16x16x32_bf16 v[160:163], v[152:155], v[184:187], 0
	s_waitcnt lgkmcnt(5)
	v_mfma_f32_16x16x32_bf16 v[136:139], v[128:131], v[192:195], 0
	v_mfma_f32_16x16x32_bf16 v[132:135], v[152:155], v[192:195], 0
	s_waitcnt lgkmcnt(3)
	v_mfma_f32_16x16x32_bf16 v[116:119], v[128:131], v[200:203], 0
	v_mfma_f32_16x16x32_bf16 v[112:115], v[152:155], v[200:203], 0
	s_waitcnt lgkmcnt(1)
	v_mfma_f32_16x16x32_bf16 v[76:79], v[128:131], v[224:227], 0
	v_mfma_f32_16x16x32_bf16 v[72:75], v[152:155], v[224:227], 0
	v_mfma_f32_16x16x32_bf16 v[164:167], v[140:143], v[188:191], v[164:167]
	v_mfma_f32_16x16x32_bf16 v[160:163], v[156:159], v[188:191], v[160:163]
	v_mfma_f32_16x16x32_bf16 v[136:139], v[140:143], v[196:199], v[136:139]
	v_mfma_f32_16x16x32_bf16 v[132:135], v[156:159], v[196:199], v[132:135]
	v_mfma_f32_16x16x32_bf16 v[116:119], v[140:143], v[204:207], v[116:119]
	v_mfma_f32_16x16x32_bf16 v[112:115], v[156:159], v[204:207], v[112:115]
	s_waitcnt lgkmcnt(0)
	v_mfma_f32_16x16x32_bf16 v[76:79], v[140:143], v[228:231], v[76:79]
	v_mfma_f32_16x16x32_bf16 v[72:75], v[156:159], v[228:231], v[72:75]
	v_mfma_f32_16x16x32_bf16 v[148:151], v[168:171], v[184:187], 0
	v_mfma_f32_16x16x32_bf16 v[144:147], v[176:179], v[184:187], 0
	v_mfma_f32_16x16x32_bf16 v[124:127], v[168:171], v[192:195], 0
	v_mfma_f32_16x16x32_bf16 v[120:123], v[176:179], v[192:195], 0
	v_mfma_f32_16x16x32_bf16 v[108:111], v[168:171], v[200:203], 0
	v_mfma_f32_16x16x32_bf16 v[104:107], v[176:179], v[200:203], 0
	v_mfma_f32_16x16x32_bf16 v[68:71], v[168:171], v[224:227], 0
	v_mfma_f32_16x16x32_bf16 v[64:67], v[176:179], v[224:227], 0
	v_mfma_f32_16x16x32_bf16 v[148:151], v[172:175], v[188:191], v[148:151]
	v_mfma_f32_16x16x32_bf16 v[144:147], v[180:183], v[188:191], v[144:147]
	v_mfma_f32_16x16x32_bf16 v[124:127], v[172:175], v[196:199], v[124:127]
	v_mfma_f32_16x16x32_bf16 v[120:123], v[180:183], v[196:199], v[120:123]
	v_mfma_f32_16x16x32_bf16 v[108:111], v[172:175], v[204:207], v[108:111]
	v_mfma_f32_16x16x32_bf16 v[104:107], v[180:183], v[204:207], v[104:107]
	v_mfma_f32_16x16x32_bf16 v[68:71], v[172:175], v[228:231], v[68:71]
	v_mfma_f32_16x16x32_bf16 v[64:67], v[180:183], v[228:231], v[64:67]
	s_barrier
	ds_read_b128 v[184:187], v223 offset:16384
	ds_read_b128 v[188:191], v223 offset:17408
	ds_read_b128 v[192:195], v223 offset:18432
	ds_read_b128 v[196:199], v223 offset:19456
	ds_read_b128 v[200:203], v223 offset:20480
	ds_read_b128 v[204:207], v223 offset:21504
	ds_read_b128 v[224:227], v223 offset:22528
	ds_read_b128 v[228:231], v223 offset:23552
	s_mov_b32 m0, s55
	s_nop 0
	buffer_load_dwordx4 v220, s[48:51], s12 offen lds
	s_add_i32 s14, s12, 0x80000
	s_mov_b32 m0, s76
	s_nop 0
	buffer_load_dwordx4 v221, s[48:51], s12 offen lds
	s_nop 0
	s_mov_b32 m0, s77
	s_nop 0
	buffer_load_dwordx4 v220, s[48:51], s14 offen lds
	s_nop 0
	s_mov_b32 m0, s78
	s_nop 0
	buffer_load_dwordx4 v221, s[48:51], s14 offen lds
	s_nop 0
	s_mov_b32 m0, s31
	s_nop 0
	buffer_load_dwordx4 v220, s[64:67], s13 offen lds
	s_nop 0
	s_mov_b32 m0, s79
	s_nop 0
	buffer_load_dwordx4 v221, s[64:67], s13 offen lds
	s_waitcnt vmcnt(24)
	s_waitcnt lgkmcnt(0)
	s_barrier
	s_waitcnt lgkmcnt(7)
	v_mfma_f32_16x16x32_bf16 v[60:63], v[128:131], v[184:187], 0
	v_mfma_f32_16x16x32_bf16 v[56:59], v[152:155], v[184:187], 0
	s_waitcnt lgkmcnt(5)
	v_mfma_f32_16x16x32_bf16 v[44:47], v[128:131], v[192:195], 0
	v_mfma_f32_16x16x32_bf16 v[40:43], v[152:155], v[192:195], 0
	s_waitcnt lgkmcnt(3)
	v_mfma_f32_16x16x32_bf16 v[28:31], v[128:131], v[200:203], 0
	v_mfma_f32_16x16x32_bf16 v[24:27], v[152:155], v[200:203], 0
	s_waitcnt lgkmcnt(1)
	v_mfma_f32_16x16x32_bf16 v[12:15], v[128:131], v[224:227], 0
	v_mfma_f32_16x16x32_bf16 v[8:11], v[152:155], v[224:227], 0
	v_mfma_f32_16x16x32_bf16 v[60:63], v[140:143], v[188:191], v[60:63]
	v_mfma_f32_16x16x32_bf16 v[56:59], v[156:159], v[188:191], v[56:59]
	v_mfma_f32_16x16x32_bf16 v[44:47], v[140:143], v[196:199], v[44:47]
	v_mfma_f32_16x16x32_bf16 v[40:43], v[156:159], v[196:199], v[40:43]
	v_mfma_f32_16x16x32_bf16 v[28:31], v[140:143], v[204:207], v[28:31]
	v_mfma_f32_16x16x32_bf16 v[24:27], v[156:159], v[204:207], v[24:27]
	s_waitcnt lgkmcnt(0)
	v_mfma_f32_16x16x32_bf16 v[12:15], v[140:143], v[228:231], v[12:15]
	v_mfma_f32_16x16x32_bf16 v[8:11], v[156:159], v[228:231], v[8:11]
	v_mfma_f32_16x16x32_bf16 v[52:55], v[168:171], v[184:187], 0
	v_mfma_f32_16x16x32_bf16 v[48:51], v[176:179], v[184:187], 0
	v_mfma_f32_16x16x32_bf16 v[36:39], v[168:171], v[192:195], 0
	v_mfma_f32_16x16x32_bf16 v[32:35], v[176:179], v[192:195], 0
	v_mfma_f32_16x16x32_bf16 v[20:23], v[168:171], v[200:203], 0
	v_mfma_f32_16x16x32_bf16 v[16:19], v[176:179], v[200:203], 0
	v_mfma_f32_16x16x32_bf16 v[4:7], v[168:171], v[224:227], 0
	v_mfma_f32_16x16x32_bf16 v[0:3], v[176:179], v[224:227], 0
	v_mfma_f32_16x16x32_bf16 v[52:55], v[172:175], v[188:191], v[52:55]
	v_mfma_f32_16x16x32_bf16 v[48:51], v[180:183], v[188:191], v[48:51]
	v_mfma_f32_16x16x32_bf16 v[36:39], v[172:175], v[196:199], v[36:39]
	v_mfma_f32_16x16x32_bf16 v[32:35], v[180:183], v[196:199], v[32:35]
	v_mfma_f32_16x16x32_bf16 v[20:23], v[172:175], v[204:207], v[20:23]
	v_mfma_f32_16x16x32_bf16 v[16:19], v[180:183], v[204:207], v[16:19]
	v_mfma_f32_16x16x32_bf16 v[4:7], v[172:175], v[228:231], v[4:7]
	v_mfma_f32_16x16x32_bf16 v[0:3], v[180:183], v[228:231], v[0:3]
	s_barrier
	v_add_u32_e32 v156, 0x18000, v222
	v_add_u32_e32 v180, 0x1c000, v222
	ds_read_b128 v[128:131], v156
	ds_read_b128 v[140:143], v156 offset:1024
	ds_read_b128 v[152:155], v156 offset:2048
	ds_read_b128 v[156:159], v156 offset:3072
	ds_read_b128 v[168:171], v180
	ds_read_b128 v[172:175], v180 offset:1024
	ds_read_b128 v[176:179], v180 offset:2048
	ds_read_b128 v[180:183], v180 offset:3072
	ds_read_b128 v[184:187], v223 offset:32768
	ds_read_b128 v[188:191], v223 offset:33792
	ds_read_b128 v[192:195], v223 offset:34816
	ds_read_b128 v[196:199], v223 offset:35840
	ds_read_b128 v[200:203], v223 offset:36864
	ds_read_b128 v[204:207], v223 offset:37888
	ds_read_b128 v[224:227], v223 offset:38912
	ds_read_b128 v[228:231], v223 offset:39936
	s_add_i32 s13, s13, 0x80000
	s_mov_b32 m0, s82
	s_nop 0
	buffer_load_dwordx4 v220, s[64:67], s13 offen lds
	s_nop 0
	s_mov_b32 m0, s83
	s_nop 0
	buffer_load_dwordx4 v221, s[64:67], s13 offen lds
	s_waitcnt vmcnt(8)
	s_waitcnt lgkmcnt(0)
	s_barrier
	s_waitcnt lgkmcnt(7)
	v_mfma_f32_16x16x32_bf16 v[164:167], v[128:131], v[184:187], v[164:167]
	v_mfma_f32_16x16x32_bf16 v[160:163], v[152:155], v[184:187], v[160:163]
	s_waitcnt lgkmcnt(5)
	v_mfma_f32_16x16x32_bf16 v[136:139], v[128:131], v[192:195], v[136:139]
	v_mfma_f32_16x16x32_bf16 v[132:135], v[152:155], v[192:195], v[132:135]
	s_waitcnt lgkmcnt(3)
	v_mfma_f32_16x16x32_bf16 v[116:119], v[128:131], v[200:203], v[116:119]
	v_mfma_f32_16x16x32_bf16 v[112:115], v[152:155], v[200:203], v[112:115]
	s_waitcnt lgkmcnt(1)
	v_mfma_f32_16x16x32_bf16 v[76:79], v[128:131], v[224:227], v[76:79]
	v_mfma_f32_16x16x32_bf16 v[72:75], v[152:155], v[224:227], v[72:75]
	v_mfma_f32_16x16x32_bf16 v[164:167], v[140:143], v[188:191], v[164:167]
	v_mfma_f32_16x16x32_bf16 v[160:163], v[156:159], v[188:191], v[160:163]
	v_mfma_f32_16x16x32_bf16 v[136:139], v[140:143], v[196:199], v[136:139]
	v_mfma_f32_16x16x32_bf16 v[132:135], v[156:159], v[196:199], v[132:135]
	v_mfma_f32_16x16x32_bf16 v[116:119], v[140:143], v[204:207], v[116:119]
	v_mfma_f32_16x16x32_bf16 v[112:115], v[156:159], v[204:207], v[112:115]
	s_waitcnt lgkmcnt(0)
	v_mfma_f32_16x16x32_bf16 v[76:79], v[140:143], v[228:231], v[76:79]
	v_mfma_f32_16x16x32_bf16 v[72:75], v[156:159], v[228:231], v[72:75]
	v_mfma_f32_16x16x32_bf16 v[148:151], v[168:171], v[184:187], v[148:151]
	v_mfma_f32_16x16x32_bf16 v[144:147], v[176:179], v[184:187], v[144:147]
	v_mfma_f32_16x16x32_bf16 v[124:127], v[168:171], v[192:195], v[124:127]
	v_mfma_f32_16x16x32_bf16 v[120:123], v[176:179], v[192:195], v[120:123]
	v_mfma_f32_16x16x32_bf16 v[108:111], v[168:171], v[200:203], v[108:111]
	v_mfma_f32_16x16x32_bf16 v[104:107], v[176:179], v[200:203], v[104:107]
	v_mfma_f32_16x16x32_bf16 v[68:71], v[168:171], v[224:227], v[68:71]
	v_mfma_f32_16x16x32_bf16 v[64:67], v[176:179], v[224:227], v[64:67]
	v_mfma_f32_16x16x32_bf16 v[148:151], v[172:175], v[188:191], v[148:151]
	v_mfma_f32_16x16x32_bf16 v[144:147], v[180:183], v[188:191], v[144:147]
	v_mfma_f32_16x16x32_bf16 v[124:127], v[172:175], v[196:199], v[124:127]
	v_mfma_f32_16x16x32_bf16 v[120:123], v[180:183], v[196:199], v[120:123]
	v_mfma_f32_16x16x32_bf16 v[108:111], v[172:175], v[204:207], v[108:111]
	v_mfma_f32_16x16x32_bf16 v[104:107], v[180:183], v[204:207], v[104:107]
	v_mfma_f32_16x16x32_bf16 v[68:71], v[172:175], v[228:231], v[68:71]
	v_mfma_f32_16x16x32_bf16 v[64:67], v[180:183], v[228:231], v[64:67]
	s_barrier
	ds_read_b128 v[184:187], v223 offset:49152
	ds_read_b128 v[188:191], v223 offset:50176
	ds_read_b128 v[192:195], v223 offset:51200
	ds_read_b128 v[196:199], v223 offset:52224
	ds_read_b128 v[200:203], v223 offset:53248
	ds_read_b128 v[204:207], v223 offset:54272
	ds_read_b128 v[224:227], v223 offset:55296
	ds_read_b128 v[228:231], v223 offset:56320
	s_or_b32 s13, s12, 0x4000
	s_mov_b32 m0, s34
	s_nop 0
	buffer_load_dwordx4 v220, s[48:51], s13 offen lds
	s_add_i32 s12, s12, 0x84000
	s_mov_b32 m0, s84
	s_nop 0
	buffer_load_dwordx4 v221, s[48:51], s13 offen lds
	s_nop 0
	s_mov_b32 m0, s87
	s_nop 0
	buffer_load_dwordx4 v220, s[48:51], s12 offen lds
	s_nop 0
	s_mov_b32 m0, s88
	s_nop 0
	buffer_load_dwordx4 v221, s[48:51], s12 offen lds
	s_nop 0
	s_mov_b32 m0, s85
	s_nop 0
	buffer_load_dwordx4 v220, s[64:67], s11 offen lds
	s_nop 0
	s_mov_b32 m0, s86
	s_nop 0
	buffer_load_dwordx4 v221, s[64:67], s11 offen lds
	s_waitcnt vmcnt(8)
	s_waitcnt lgkmcnt(0)
	s_barrier
	s_waitcnt lgkmcnt(7)
	v_mfma_f32_16x16x32_bf16 v[60:63], v[128:131], v[184:187], v[60:63]
	v_mfma_f32_16x16x32_bf16 v[56:59], v[152:155], v[184:187], v[56:59]
	s_waitcnt lgkmcnt(5)
	v_mfma_f32_16x16x32_bf16 v[44:47], v[128:131], v[192:195], v[44:47]
	v_mfma_f32_16x16x32_bf16 v[40:43], v[152:155], v[192:195], v[40:43]
	s_waitcnt lgkmcnt(3)
	v_mfma_f32_16x16x32_bf16 v[28:31], v[128:131], v[200:203], v[28:31]
	v_mfma_f32_16x16x32_bf16 v[24:27], v[152:155], v[200:203], v[24:27]
	s_waitcnt lgkmcnt(1)
	v_mfma_f32_16x16x32_bf16 v[12:15], v[128:131], v[224:227], v[12:15]
	v_mfma_f32_16x16x32_bf16 v[8:11], v[152:155], v[224:227], v[8:11]
	v_mfma_f32_16x16x32_bf16 v[60:63], v[140:143], v[188:191], v[60:63]
	v_mfma_f32_16x16x32_bf16 v[56:59], v[156:159], v[188:191], v[56:59]
	v_mfma_f32_16x16x32_bf16 v[44:47], v[140:143], v[196:199], v[44:47]
	v_mfma_f32_16x16x32_bf16 v[40:43], v[156:159], v[196:199], v[40:43]
	v_mfma_f32_16x16x32_bf16 v[28:31], v[140:143], v[204:207], v[28:31]
	v_mfma_f32_16x16x32_bf16 v[24:27], v[156:159], v[204:207], v[24:27]
	s_waitcnt lgkmcnt(0)
	v_mfma_f32_16x16x32_bf16 v[12:15], v[140:143], v[228:231], v[12:15]
	v_mfma_f32_16x16x32_bf16 v[8:11], v[156:159], v[228:231], v[8:11]
	v_mfma_f32_16x16x32_bf16 v[52:55], v[168:171], v[184:187], v[52:55]
	v_mfma_f32_16x16x32_bf16 v[48:51], v[176:179], v[184:187], v[48:51]
	v_mfma_f32_16x16x32_bf16 v[36:39], v[168:171], v[192:195], v[36:39]
	v_mfma_f32_16x16x32_bf16 v[32:35], v[176:179], v[192:195], v[32:35]
	v_mfma_f32_16x16x32_bf16 v[20:23], v[168:171], v[200:203], v[20:23]
	v_mfma_f32_16x16x32_bf16 v[16:19], v[176:179], v[200:203], v[16:19]
	v_mfma_f32_16x16x32_bf16 v[4:7], v[168:171], v[224:227], v[4:7]
	v_mfma_f32_16x16x32_bf16 v[0:3], v[176:179], v[224:227], v[0:3]
	v_mfma_f32_16x16x32_bf16 v[52:55], v[172:175], v[188:191], v[52:55]
	v_mfma_f32_16x16x32_bf16 v[48:51], v[180:183], v[188:191], v[48:51]
	v_mfma_f32_16x16x32_bf16 v[36:39], v[172:175], v[196:199], v[36:39]
	v_mfma_f32_16x16x32_bf16 v[32:35], v[180:183], v[196:199], v[32:35]
	v_mfma_f32_16x16x32_bf16 v[20:23], v[172:175], v[204:207], v[20:23]
	v_mfma_f32_16x16x32_bf16 v[16:19], v[180:183], v[204:207], v[16:19]
	v_mfma_f32_16x16x32_bf16 v[4:7], v[172:175], v[228:231], v[4:7]
	v_mfma_f32_16x16x32_bf16 v[0:3], v[180:183], v[228:231], v[0:3]
	s_barrier
	s_add_i32 s10, s10, 2
	s_add_i32 s8, s8, 0x8000
	s_add_i32 s9, s9, 0x8000
	.p2align	6

.Lnb_p5:
	s_add_i32 s53, s37, 0xfff84000
	s_cmp_eq_u32 s52, 28
	s_cselect_b32 s56, s4, s53
	s_cselect_b32 s55, s5, s51
	s_or_b32 s53, s56, 0x4000
	s_mov_b32 m0, s41
	s_nop 0
	buffer_load_dwordx4 v166, s[24:27], s37 offen lds
	s_nop 0
	s_mov_b32 m0, s42
	s_nop 0
	buffer_load_dwordx4 v167, s[24:27], s37 offen lds
	s_waitcnt vmcnt(24)
	s_waitcnt lgkmcnt(0)
	s_barrier
	s_waitcnt lgkmcnt(7)
	v_mfma_f32_16x16x32_bf16 v[148:151], v[152:155], v[190:193], 0
	v_mfma_f32_16x16x32_bf16 v[140:143], v[160:163], v[190:193], 0
	s_waitcnt lgkmcnt(5)
	v_mfma_f32_16x16x32_bf16 v[132:135], v[152:155], v[198:201], 0
	v_mfma_f32_16x16x32_bf16 v[124:127], v[160:163], v[198:201], 0
	s_waitcnt lgkmcnt(3)
	v_mfma_f32_16x16x32_bf16 v[116:119], v[152:155], v[220:223], 0
	v_mfma_f32_16x16x32_bf16 v[108:111], v[160:163], v[220:223], 0
	s_waitcnt lgkmcnt(1)
	v_mfma_f32_16x16x32_bf16 v[76:79], v[152:155], v[228:231], 0
	v_mfma_f32_16x16x32_bf16 v[68:71], v[160:163], v[228:231], 0
	v_mfma_f32_16x16x32_bf16 v[148:151], v[156:159], v[194:197], v[148:151]
	v_mfma_f32_16x16x32_bf16 v[140:143], v[170:173], v[194:197], v[140:143]
	v_mfma_f32_16x16x32_bf16 v[132:135], v[156:159], v[202:205], v[132:135]
	v_mfma_f32_16x16x32_bf16 v[124:127], v[170:173], v[202:205], v[124:127]
	v_mfma_f32_16x16x32_bf16 v[116:119], v[156:159], v[224:227], v[116:119]
	v_mfma_f32_16x16x32_bf16 v[108:111], v[170:173], v[224:227], v[108:111]
	s_waitcnt lgkmcnt(0)
	v_mfma_f32_16x16x32_bf16 v[76:79], v[156:159], v[240:243], v[76:79]
	v_mfma_f32_16x16x32_bf16 v[68:71], v[170:173], v[240:243], v[68:71]
	v_mfma_f32_16x16x32_bf16 v[144:147], v[174:177], v[190:193], 0
	v_mfma_f32_16x16x32_bf16 v[136:139], v[182:185], v[190:193], 0
	v_mfma_f32_16x16x32_bf16 v[128:131], v[174:177], v[198:201], 0
	v_mfma_f32_16x16x32_bf16 v[120:123], v[182:185], v[198:201], 0
	v_mfma_f32_16x16x32_bf16 v[112:115], v[174:177], v[220:223], 0
	v_mfma_f32_16x16x32_bf16 v[104:107], v[182:185], v[220:223], 0
	v_mfma_f32_16x16x32_bf16 v[72:75], v[174:177], v[228:231], 0
	v_mfma_f32_16x16x32_bf16 v[64:67], v[182:185], v[228:231], 0
	v_mfma_f32_16x16x32_bf16 v[144:147], v[178:181], v[194:197], v[144:147]
	v_mfma_f32_16x16x32_bf16 v[136:139], v[186:189], v[194:197], v[136:139]
	v_mfma_f32_16x16x32_bf16 v[128:131], v[178:181], v[202:205], v[128:131]
	v_mfma_f32_16x16x32_bf16 v[120:123], v[186:189], v[202:205], v[120:123]
	v_mfma_f32_16x16x32_bf16 v[112:115], v[178:181], v[224:227], v[112:115]
	v_mfma_f32_16x16x32_bf16 v[104:107], v[186:189], v[224:227], v[104:107]
	v_mfma_f32_16x16x32_bf16 v[72:75], v[178:181], v[240:243], v[72:75]
	v_mfma_f32_16x16x32_bf16 v[64:67], v[186:189], v[240:243], v[64:67]
	s_barrier
	ds_read_b128 v[190:193], v169 offset:16384
	ds_read_b128 v[194:197], v169 offset:17408
	ds_read_b128 v[198:201], v169 offset:18432
	ds_read_b128 v[202:205], v169 offset:19456
	ds_read_b128 v[220:223], v169 offset:20480
	ds_read_b128 v[224:227], v169 offset:21504
	ds_read_b128 v[228:231], v169 offset:22528
	ds_read_b128 v[240:243], v169 offset:23552
	s_mov_b32 m0, s7
	s_nop 0
	buffer_load_dwordx4 v166, s[28:31], s55 offen lds
	s_add_i32 s57, s55, 0x80000
	s_mov_b32 m0, s8
	s_nop 0
	buffer_load_dwordx4 v167, s[28:31], s55 offen lds
	s_nop 0
	s_mov_b32 m0, s9
	s_nop 0
	buffer_load_dwordx4 v166, s[28:31], s57 offen lds
	s_nop 0
	s_mov_b32 m0, s10
	s_nop 0
	buffer_load_dwordx4 v167, s[28:31], s57 offen lds
	s_nop 0
	s_mov_b32 m0, s6
	s_nop 0
	buffer_load_dwordx4 v166, s[24:27], s56 offen lds
	s_nop 0
	s_mov_b32 m0, s11
	s_nop 0
	buffer_load_dwordx4 v167, s[24:27], s56 offen lds
	s_waitcnt vmcnt(24)
	s_waitcnt lgkmcnt(0)
	s_barrier
	s_waitcnt lgkmcnt(7)
	v_mfma_f32_16x16x32_bf16 v[60:63], v[152:155], v[190:193], 0
	v_mfma_f32_16x16x32_bf16 v[52:55], v[160:163], v[190:193], 0
	s_waitcnt lgkmcnt(5)
	v_mfma_f32_16x16x32_bf16 v[44:47], v[152:155], v[198:201], 0
	v_mfma_f32_16x16x32_bf16 v[36:39], v[160:163], v[198:201], 0
	s_waitcnt lgkmcnt(3)
	v_mfma_f32_16x16x32_bf16 v[28:31], v[152:155], v[220:223], 0
	v_mfma_f32_16x16x32_bf16 v[20:23], v[160:163], v[220:223], 0
	s_waitcnt lgkmcnt(1)
	v_mfma_f32_16x16x32_bf16 v[12:15], v[152:155], v[228:231], 0
	v_mfma_f32_16x16x32_bf16 v[4:7], v[160:163], v[228:231], 0
	v_mfma_f32_16x16x32_bf16 v[60:63], v[156:159], v[194:197], v[60:63]
	v_mfma_f32_16x16x32_bf16 v[52:55], v[170:173], v[194:197], v[52:55]
	v_mfma_f32_16x16x32_bf16 v[44:47], v[156:159], v[202:205], v[44:47]
	v_mfma_f32_16x16x32_bf16 v[36:39], v[170:173], v[202:205], v[36:39]
	v_mfma_f32_16x16x32_bf16 v[28:31], v[156:159], v[224:227], v[28:31]
	v_mfma_f32_16x16x32_bf16 v[20:23], v[170:173], v[224:227], v[20:23]
	s_waitcnt lgkmcnt(0)
	v_mfma_f32_16x16x32_bf16 v[12:15], v[156:159], v[240:243], v[12:15]
	v_mfma_f32_16x16x32_bf16 v[4:7], v[170:173], v[240:243], v[4:7]
	v_mfma_f32_16x16x32_bf16 v[56:59], v[174:177], v[190:193], 0
	v_mfma_f32_16x16x32_bf16 v[48:51], v[182:185], v[190:193], 0
	v_mfma_f32_16x16x32_bf16 v[40:43], v[174:177], v[198:201], 0
	v_mfma_f32_16x16x32_bf16 v[32:35], v[182:185], v[198:201], 0
	v_mfma_f32_16x16x32_bf16 v[24:27], v[174:177], v[220:223], 0
	v_mfma_f32_16x16x32_bf16 v[16:19], v[182:185], v[220:223], 0
	v_mfma_f32_16x16x32_bf16 v[8:11], v[174:177], v[228:231], 0
	v_mfma_f32_16x16x32_bf16 v[0:3], v[182:185], v[228:231], 0
	v_mfma_f32_16x16x32_bf16 v[56:59], v[178:181], v[194:197], v[56:59]
	v_mfma_f32_16x16x32_bf16 v[48:51], v[186:189], v[194:197], v[48:51]
	v_mfma_f32_16x16x32_bf16 v[40:43], v[178:181], v[202:205], v[40:43]
	v_mfma_f32_16x16x32_bf16 v[32:35], v[186:189], v[202:205], v[32:35]
	v_mfma_f32_16x16x32_bf16 v[24:27], v[178:181], v[224:227], v[24:27]
	v_mfma_f32_16x16x32_bf16 v[16:19], v[186:189], v[224:227], v[16:19]
	v_mfma_f32_16x16x32_bf16 v[8:11], v[178:181], v[240:243], v[8:11]
	v_mfma_f32_16x16x32_bf16 v[0:3], v[186:189], v[240:243], v[0:3]
	s_barrier
	v_add_u32_e32 v164, 0x18000, v168
	ds_read_b128 v[152:155], v164
	ds_read_b128 v[156:159], v164 offset:1024
	ds_read_b128 v[160:163], v164 offset:2048
	ds_read_b128 v[170:173], v164 offset:3072
	v_add_u32_e32 v164, 0x1c000, v168
	ds_read_b128 v[174:177], v164
	ds_read_b128 v[178:181], v164 offset:1024
	ds_read_b128 v[182:185], v164 offset:2048
	ds_read_b128 v[186:189], v164 offset:3072
	ds_read_b128 v[190:193], v169 offset:32768
	ds_read_b128 v[194:197], v169 offset:33792
	ds_read_b128 v[198:201], v169 offset:34816
	ds_read_b128 v[202:205], v169 offset:35840
	ds_read_b128 v[220:223], v169 offset:36864
	ds_read_b128 v[224:227], v169 offset:37888
	ds_read_b128 v[228:231], v169 offset:38912
	ds_read_b128 v[240:243], v169 offset:39936
	s_add_i32 s56, s56, 0x80000
	s_mov_b32 m0, s12
	s_nop 0
	buffer_load_dwordx4 v166, s[24:27], s56 offen lds
	s_nop 0
	s_mov_b32 m0, s13
	s_nop 0
	buffer_load_dwordx4 v167, s[24:27], s56 offen lds
	s_waitcnt vmcnt(8)
	s_waitcnt lgkmcnt(0)
	s_barrier
	s_waitcnt lgkmcnt(7)
	v_mfma_f32_16x16x32_bf16 v[148:151], v[152:155], v[190:193], v[148:151]
	v_mfma_f32_16x16x32_bf16 v[140:143], v[160:163], v[190:193], v[140:143]
	s_waitcnt lgkmcnt(5)
	v_mfma_f32_16x16x32_bf16 v[132:135], v[152:155], v[198:201], v[132:135]
	v_mfma_f32_16x16x32_bf16 v[124:127], v[160:163], v[198:201], v[124:127]
	s_waitcnt lgkmcnt(3)
	v_mfma_f32_16x16x32_bf16 v[116:119], v[152:155], v[220:223], v[116:119]
	v_mfma_f32_16x16x32_bf16 v[108:111], v[160:163], v[220:223], v[108:111]
	s_waitcnt lgkmcnt(1)
	v_mfma_f32_16x16x32_bf16 v[76:79], v[152:155], v[228:231], v[76:79]
	v_mfma_f32_16x16x32_bf16 v[68:71], v[160:163], v[228:231], v[68:71]
	v_mfma_f32_16x16x32_bf16 v[148:151], v[156:159], v[194:197], v[148:151]
	v_mfma_f32_16x16x32_bf16 v[140:143], v[170:173], v[194:197], v[140:143]
	v_mfma_f32_16x16x32_bf16 v[132:135], v[156:159], v[202:205], v[132:135]
	v_mfma_f32_16x16x32_bf16 v[124:127], v[170:173], v[202:205], v[124:127]
	v_mfma_f32_16x16x32_bf16 v[116:119], v[156:159], v[224:227], v[116:119]
	v_mfma_f32_16x16x32_bf16 v[108:111], v[170:173], v[224:227], v[108:111]
	s_waitcnt lgkmcnt(0)
	v_mfma_f32_16x16x32_bf16 v[76:79], v[156:159], v[240:243], v[76:79]
	v_mfma_f32_16x16x32_bf16 v[68:71], v[170:173], v[240:243], v[68:71]
	v_mfma_f32_16x16x32_bf16 v[144:147], v[174:177], v[190:193], v[144:147]
	v_mfma_f32_16x16x32_bf16 v[136:139], v[182:185], v[190:193], v[136:139]
	v_mfma_f32_16x16x32_bf16 v[128:131], v[174:177], v[198:201], v[128:131]
	v_mfma_f32_16x16x32_bf16 v[120:123], v[182:185], v[198:201], v[120:123]
	v_mfma_f32_16x16x32_bf16 v[112:115], v[174:177], v[220:223], v[112:115]
	v_mfma_f32_16x16x32_bf16 v[104:107], v[182:185], v[220:223], v[104:107]
	v_mfma_f32_16x16x32_bf16 v[72:75], v[174:177], v[228:231], v[72:75]
	v_mfma_f32_16x16x32_bf16 v[64:67], v[182:185], v[228:231], v[64:67]
	v_mfma_f32_16x16x32_bf16 v[144:147], v[178:181], v[194:197], v[144:147]
	v_mfma_f32_16x16x32_bf16 v[136:139], v[186:189], v[194:197], v[136:139]
	v_mfma_f32_16x16x32_bf16 v[128:131], v[178:181], v[202:205], v[128:131]
	v_mfma_f32_16x16x32_bf16 v[120:123], v[186:189], v[202:205], v[120:123]
	v_mfma_f32_16x16x32_bf16 v[112:115], v[178:181], v[224:227], v[112:115]
	v_mfma_f32_16x16x32_bf16 v[104:107], v[186:189], v[224:227], v[104:107]
	v_mfma_f32_16x16x32_bf16 v[72:75], v[178:181], v[240:243], v[72:75]
	v_mfma_f32_16x16x32_bf16 v[64:67], v[186:189], v[240:243], v[64:67]
	s_barrier
	ds_read_b128 v[190:193], v169 offset:49152
	ds_read_b128 v[194:197], v169 offset:50176
	ds_read_b128 v[198:201], v169 offset:51200
	ds_read_b128 v[202:205], v169 offset:52224
	ds_read_b128 v[220:223], v169 offset:53248
	ds_read_b128 v[224:227], v169 offset:54272
	ds_read_b128 v[228:231], v169 offset:55296
	ds_read_b128 v[240:243], v169 offset:56320
	s_or_b32 s56, s55, 0x4000
	s_mov_b32 m0, s16
	s_nop 0
	buffer_load_dwordx4 v166, s[28:31], s56 offen lds
	s_add_i32 s55, s55, 0x84000
	s_mov_b32 m0, s17
	s_nop 0
	buffer_load_dwordx4 v167, s[28:31], s56 offen lds
	s_nop 0
	s_mov_b32 m0, s34
	s_nop 0
	buffer_load_dwordx4 v166, s[28:31], s55 offen lds
	s_nop 0
	s_mov_b32 m0, s40
	s_nop 0
	buffer_load_dwordx4 v167, s[28:31], s55 offen lds
	s_nop 0
	s_mov_b32 m0, s18
	s_nop 0
	buffer_load_dwordx4 v166, s[24:27], s53 offen lds
	s_nop 0
	s_mov_b32 m0, s19
	s_nop 0
	buffer_load_dwordx4 v167, s[24:27], s53 offen lds
	s_waitcnt vmcnt(8)
	s_waitcnt lgkmcnt(0)
	s_barrier
	s_waitcnt lgkmcnt(7)
	v_mfma_f32_16x16x32_bf16 v[60:63], v[152:155], v[190:193], v[60:63]
	v_mfma_f32_16x16x32_bf16 v[52:55], v[160:163], v[190:193], v[52:55]
	s_waitcnt lgkmcnt(5)
	v_mfma_f32_16x16x32_bf16 v[44:47], v[152:155], v[198:201], v[44:47]
	v_mfma_f32_16x16x32_bf16 v[36:39], v[160:163], v[198:201], v[36:39]
	s_waitcnt lgkmcnt(3)
	v_mfma_f32_16x16x32_bf16 v[28:31], v[152:155], v[220:223], v[28:31]
	v_mfma_f32_16x16x32_bf16 v[20:23], v[160:163], v[220:223], v[20:23]
	s_waitcnt lgkmcnt(1)
	v_mfma_f32_16x16x32_bf16 v[12:15], v[152:155], v[228:231], v[12:15]
	v_mfma_f32_16x16x32_bf16 v[4:7], v[160:163], v[228:231], v[4:7]
	v_mfma_f32_16x16x32_bf16 v[60:63], v[156:159], v[194:197], v[60:63]
	v_mfma_f32_16x16x32_bf16 v[52:55], v[170:173], v[194:197], v[52:55]
	v_mfma_f32_16x16x32_bf16 v[44:47], v[156:159], v[202:205], v[44:47]
	v_mfma_f32_16x16x32_bf16 v[36:39], v[170:173], v[202:205], v[36:39]
	v_mfma_f32_16x16x32_bf16 v[28:31], v[156:159], v[224:227], v[28:31]
	v_mfma_f32_16x16x32_bf16 v[20:23], v[170:173], v[224:227], v[20:23]
	s_waitcnt lgkmcnt(0)
	v_mfma_f32_16x16x32_bf16 v[12:15], v[156:159], v[240:243], v[12:15]
	v_mfma_f32_16x16x32_bf16 v[4:7], v[170:173], v[240:243], v[4:7]
	v_mfma_f32_16x16x32_bf16 v[56:59], v[174:177], v[190:193], v[56:59]
	v_mfma_f32_16x16x32_bf16 v[48:51], v[182:185], v[190:193], v[48:51]
	v_mfma_f32_16x16x32_bf16 v[40:43], v[174:177], v[198:201], v[40:43]
	v_mfma_f32_16x16x32_bf16 v[32:35], v[182:185], v[198:201], v[32:35]
	v_mfma_f32_16x16x32_bf16 v[24:27], v[174:177], v[220:223], v[24:27]
	v_mfma_f32_16x16x32_bf16 v[16:19], v[182:185], v[220:223], v[16:19]
	v_mfma_f32_16x16x32_bf16 v[8:11], v[174:177], v[228:231], v[8:11]
	v_mfma_f32_16x16x32_bf16 v[0:3], v[182:185], v[228:231], v[0:3]
	v_mfma_f32_16x16x32_bf16 v[56:59], v[178:181], v[194:197], v[56:59]
	v_mfma_f32_16x16x32_bf16 v[48:51], v[186:189], v[194:197], v[48:51]
	v_mfma_f32_16x16x32_bf16 v[40:43], v[178:181], v[202:205], v[40:43]
	v_mfma_f32_16x16x32_bf16 v[32:35], v[186:189], v[202:205], v[32:35]
	v_mfma_f32_16x16x32_bf16 v[24:27], v[178:181], v[224:227], v[24:27]
	v_mfma_f32_16x16x32_bf16 v[16:19], v[186:189], v[224:227], v[16:19]
	v_mfma_f32_16x16x32_bf16 v[8:11], v[178:181], v[240:243], v[8:11]
	v_mfma_f32_16x16x32_bf16 v[0:3], v[186:189], v[240:243], v[0:3]
	s_barrier
	s_add_i32 s52, s52, 2
	s_add_i32 s37, s37, 0x8000
	s_add_i32 s51, s51, 0x8000
	.p2align	6

.Lnb_p6:
	s_add_i32 s11, s8, 0xffea4000
	s_cmpk_eq_i32 s10, 0x54
	s_cselect_b32 s13, s6, s11
	s_cselect_b32 s12, s7, s9
	s_or_b32 s11, s13, 0x4000
	s_mov_b32 m0, s87
	s_nop 0
	buffer_load_dwordx4 v220, s[20:23], s8 offen lds
	s_nop 0
	s_mov_b32 m0, s89
	s_nop 0
	buffer_load_dwordx4 v221, s[20:23], s8 offen lds
	s_waitcnt vmcnt(24)
	s_waitcnt lgkmcnt(0)
	s_barrier
	s_waitcnt lgkmcnt(7)
	v_mfma_f32_16x16x32_bf16 v[164:167], v[128:131], v[184:187], 0
	v_mfma_f32_16x16x32_bf16 v[160:163], v[152:155], v[184:187], 0
	s_waitcnt lgkmcnt(5)
	v_mfma_f32_16x16x32_bf16 v[136:139], v[128:131], v[192:195], 0
	v_mfma_f32_16x16x32_bf16 v[132:135], v[152:155], v[192:195], 0
	s_waitcnt lgkmcnt(3)
	v_mfma_f32_16x16x32_bf16 v[116:119], v[128:131], v[200:203], 0
	v_mfma_f32_16x16x32_bf16 v[112:115], v[152:155], v[200:203], 0
	s_waitcnt lgkmcnt(1)
	v_mfma_f32_16x16x32_bf16 v[76:79], v[128:131], v[224:227], 0
	v_mfma_f32_16x16x32_bf16 v[72:75], v[152:155], v[224:227], 0
	v_mfma_f32_16x16x32_bf16 v[164:167], v[140:143], v[188:191], v[164:167]
	v_mfma_f32_16x16x32_bf16 v[160:163], v[156:159], v[188:191], v[160:163]
	v_mfma_f32_16x16x32_bf16 v[136:139], v[140:143], v[196:199], v[136:139]
	v_mfma_f32_16x16x32_bf16 v[132:135], v[156:159], v[196:199], v[132:135]
	v_mfma_f32_16x16x32_bf16 v[116:119], v[140:143], v[204:207], v[116:119]
	v_mfma_f32_16x16x32_bf16 v[112:115], v[156:159], v[204:207], v[112:115]
	s_waitcnt lgkmcnt(0)
	v_mfma_f32_16x16x32_bf16 v[76:79], v[140:143], v[228:231], v[76:79]
	v_mfma_f32_16x16x32_bf16 v[72:75], v[156:159], v[228:231], v[72:75]
	v_mfma_f32_16x16x32_bf16 v[148:151], v[168:171], v[184:187], 0
	v_mfma_f32_16x16x32_bf16 v[144:147], v[176:179], v[184:187], 0
	v_mfma_f32_16x16x32_bf16 v[124:127], v[168:171], v[192:195], 0
	v_mfma_f32_16x16x32_bf16 v[120:123], v[176:179], v[192:195], 0
	v_mfma_f32_16x16x32_bf16 v[108:111], v[168:171], v[200:203], 0
	v_mfma_f32_16x16x32_bf16 v[104:107], v[176:179], v[200:203], 0
	v_mfma_f32_16x16x32_bf16 v[68:71], v[168:171], v[224:227], 0
	v_mfma_f32_16x16x32_bf16 v[64:67], v[176:179], v[224:227], 0
	v_mfma_f32_16x16x32_bf16 v[148:151], v[172:175], v[188:191], v[148:151]
	v_mfma_f32_16x16x32_bf16 v[144:147], v[180:183], v[188:191], v[144:147]
	v_mfma_f32_16x16x32_bf16 v[124:127], v[172:175], v[196:199], v[124:127]
	v_mfma_f32_16x16x32_bf16 v[120:123], v[180:183], v[196:199], v[120:123]
	v_mfma_f32_16x16x32_bf16 v[108:111], v[172:175], v[204:207], v[108:111]
	v_mfma_f32_16x16x32_bf16 v[104:107], v[180:183], v[204:207], v[104:107]
	v_mfma_f32_16x16x32_bf16 v[68:71], v[172:175], v[228:231], v[68:71]
	v_mfma_f32_16x16x32_bf16 v[64:67], v[180:183], v[228:231], v[64:67]
	s_barrier
	ds_read_b128 v[184:187], v223 offset:16384
	ds_read_b128 v[188:191], v223 offset:17408
	ds_read_b128 v[192:195], v223 offset:18432
	ds_read_b128 v[196:199], v223 offset:19456
	ds_read_b128 v[200:203], v223 offset:20480
	ds_read_b128 v[204:207], v223 offset:21504
	ds_read_b128 v[224:227], v223 offset:22528
	ds_read_b128 v[228:231], v223 offset:23552
	s_mov_b32 m0, s51
	s_nop 0
	buffer_load_dwordx4 v220, s[52:55], s12 offen lds
	s_add_i32 s14, s12, 0x160000
	s_mov_b32 m0, s74
	s_nop 0
	buffer_load_dwordx4 v221, s[52:55], s12 offen lds
	s_nop 0
	s_mov_b32 m0, s75
	s_nop 0
	buffer_load_dwordx4 v220, s[52:55], s14 offen lds
	s_nop 0
	s_mov_b32 m0, s76
	s_nop 0
	buffer_load_dwordx4 v221, s[52:55], s14 offen lds
	s_nop 0
	s_mov_b32 m0, s31
	s_nop 0
	buffer_load_dwordx4 v220, s[20:23], s13 offen lds
	s_nop 0
	s_mov_b32 m0, s77
	s_nop 0
	buffer_load_dwordx4 v221, s[20:23], s13 offen lds
	s_waitcnt vmcnt(24)
	s_waitcnt lgkmcnt(0)
	s_barrier
	s_waitcnt lgkmcnt(7)
	v_mfma_f32_16x16x32_bf16 v[60:63], v[128:131], v[184:187], 0
	v_mfma_f32_16x16x32_bf16 v[56:59], v[152:155], v[184:187], 0
	s_waitcnt lgkmcnt(5)
	v_mfma_f32_16x16x32_bf16 v[44:47], v[128:131], v[192:195], 0
	v_mfma_f32_16x16x32_bf16 v[40:43], v[152:155], v[192:195], 0
	s_waitcnt lgkmcnt(3)
	v_mfma_f32_16x16x32_bf16 v[28:31], v[128:131], v[200:203], 0
	v_mfma_f32_16x16x32_bf16 v[24:27], v[152:155], v[200:203], 0
	s_waitcnt lgkmcnt(1)
	v_mfma_f32_16x16x32_bf16 v[12:15], v[128:131], v[224:227], 0
	v_mfma_f32_16x16x32_bf16 v[8:11], v[152:155], v[224:227], 0
	v_mfma_f32_16x16x32_bf16 v[60:63], v[140:143], v[188:191], v[60:63]
	v_mfma_f32_16x16x32_bf16 v[56:59], v[156:159], v[188:191], v[56:59]
	v_mfma_f32_16x16x32_bf16 v[44:47], v[140:143], v[196:199], v[44:47]
	v_mfma_f32_16x16x32_bf16 v[40:43], v[156:159], v[196:199], v[40:43]
	v_mfma_f32_16x16x32_bf16 v[28:31], v[140:143], v[204:207], v[28:31]
	v_mfma_f32_16x16x32_bf16 v[24:27], v[156:159], v[204:207], v[24:27]
	s_waitcnt lgkmcnt(0)
	v_mfma_f32_16x16x32_bf16 v[12:15], v[140:143], v[228:231], v[12:15]
	v_mfma_f32_16x16x32_bf16 v[8:11], v[156:159], v[228:231], v[8:11]
	v_mfma_f32_16x16x32_bf16 v[52:55], v[168:171], v[184:187], 0
	v_mfma_f32_16x16x32_bf16 v[48:51], v[176:179], v[184:187], 0
	v_mfma_f32_16x16x32_bf16 v[36:39], v[168:171], v[192:195], 0
	v_mfma_f32_16x16x32_bf16 v[32:35], v[176:179], v[192:195], 0
	v_mfma_f32_16x16x32_bf16 v[20:23], v[168:171], v[200:203], 0
	v_mfma_f32_16x16x32_bf16 v[16:19], v[176:179], v[200:203], 0
	v_mfma_f32_16x16x32_bf16 v[4:7], v[168:171], v[224:227], 0
	v_mfma_f32_16x16x32_bf16 v[0:3], v[176:179], v[224:227], 0
	v_mfma_f32_16x16x32_bf16 v[52:55], v[172:175], v[188:191], v[52:55]
	v_mfma_f32_16x16x32_bf16 v[48:51], v[180:183], v[188:191], v[48:51]
	v_mfma_f32_16x16x32_bf16 v[36:39], v[172:175], v[196:199], v[36:39]
	v_mfma_f32_16x16x32_bf16 v[32:35], v[180:183], v[196:199], v[32:35]
	v_mfma_f32_16x16x32_bf16 v[20:23], v[172:175], v[204:207], v[20:23]
	v_mfma_f32_16x16x32_bf16 v[16:19], v[180:183], v[204:207], v[16:19]
	v_mfma_f32_16x16x32_bf16 v[4:7], v[172:175], v[228:231], v[4:7]
	v_mfma_f32_16x16x32_bf16 v[0:3], v[180:183], v[228:231], v[0:3]
	s_barrier
	v_add_u32_e32 v156, 0x18000, v222
	v_add_u32_e32 v180, 0x1c000, v222
	ds_read_b128 v[128:131], v156
	ds_read_b128 v[140:143], v156 offset:1024
	ds_read_b128 v[152:155], v156 offset:2048
	ds_read_b128 v[156:159], v156 offset:3072
	ds_read_b128 v[168:171], v180
	ds_read_b128 v[172:175], v180 offset:1024
	ds_read_b128 v[176:179], v180 offset:2048
	ds_read_b128 v[180:183], v180 offset:3072
	ds_read_b128 v[184:187], v223 offset:32768
	ds_read_b128 v[188:191], v223 offset:33792
	ds_read_b128 v[192:195], v223 offset:34816
	ds_read_b128 v[196:199], v223 offset:35840
	ds_read_b128 v[200:203], v223 offset:36864
	ds_read_b128 v[204:207], v223 offset:37888
	ds_read_b128 v[224:227], v223 offset:38912
	ds_read_b128 v[228:231], v223 offset:39936
	s_add_i32 s13, s13, 0x160000
	s_mov_b32 m0, s78
	s_nop 0
	buffer_load_dwordx4 v220, s[20:23], s13 offen lds
	s_nop 0
	s_mov_b32 m0, s79
	s_nop 0
	buffer_load_dwordx4 v221, s[20:23], s13 offen lds
	s_waitcnt vmcnt(8)
	s_waitcnt lgkmcnt(0)
	s_barrier
	s_waitcnt lgkmcnt(7)
	v_mfma_f32_16x16x32_bf16 v[164:167], v[128:131], v[184:187], v[164:167]
	v_mfma_f32_16x16x32_bf16 v[160:163], v[152:155], v[184:187], v[160:163]
	s_waitcnt lgkmcnt(5)
	v_mfma_f32_16x16x32_bf16 v[136:139], v[128:131], v[192:195], v[136:139]
	v_mfma_f32_16x16x32_bf16 v[132:135], v[152:155], v[192:195], v[132:135]
	s_waitcnt lgkmcnt(3)
	v_mfma_f32_16x16x32_bf16 v[116:119], v[128:131], v[200:203], v[116:119]
	v_mfma_f32_16x16x32_bf16 v[112:115], v[152:155], v[200:203], v[112:115]
	s_waitcnt lgkmcnt(1)
	v_mfma_f32_16x16x32_bf16 v[76:79], v[128:131], v[224:227], v[76:79]
	v_mfma_f32_16x16x32_bf16 v[72:75], v[152:155], v[224:227], v[72:75]
	v_mfma_f32_16x16x32_bf16 v[164:167], v[140:143], v[188:191], v[164:167]
	v_mfma_f32_16x16x32_bf16 v[160:163], v[156:159], v[188:191], v[160:163]
	v_mfma_f32_16x16x32_bf16 v[136:139], v[140:143], v[196:199], v[136:139]
	v_mfma_f32_16x16x32_bf16 v[132:135], v[156:159], v[196:199], v[132:135]
	v_mfma_f32_16x16x32_bf16 v[116:119], v[140:143], v[204:207], v[116:119]
	v_mfma_f32_16x16x32_bf16 v[112:115], v[156:159], v[204:207], v[112:115]
	s_waitcnt lgkmcnt(0)
	v_mfma_f32_16x16x32_bf16 v[76:79], v[140:143], v[228:231], v[76:79]
	v_mfma_f32_16x16x32_bf16 v[72:75], v[156:159], v[228:231], v[72:75]
	v_mfma_f32_16x16x32_bf16 v[148:151], v[168:171], v[184:187], v[148:151]
	v_mfma_f32_16x16x32_bf16 v[144:147], v[176:179], v[184:187], v[144:147]
	v_mfma_f32_16x16x32_bf16 v[124:127], v[168:171], v[192:195], v[124:127]
	v_mfma_f32_16x16x32_bf16 v[120:123], v[176:179], v[192:195], v[120:123]
	v_mfma_f32_16x16x32_bf16 v[108:111], v[168:171], v[200:203], v[108:111]
	v_mfma_f32_16x16x32_bf16 v[104:107], v[176:179], v[200:203], v[104:107]
	v_mfma_f32_16x16x32_bf16 v[68:71], v[168:171], v[224:227], v[68:71]
	v_mfma_f32_16x16x32_bf16 v[64:67], v[176:179], v[224:227], v[64:67]
	v_mfma_f32_16x16x32_bf16 v[148:151], v[172:175], v[188:191], v[148:151]
	v_mfma_f32_16x16x32_bf16 v[144:147], v[180:183], v[188:191], v[144:147]
	v_mfma_f32_16x16x32_bf16 v[124:127], v[172:175], v[196:199], v[124:127]
	v_mfma_f32_16x16x32_bf16 v[120:123], v[180:183], v[196:199], v[120:123]
	v_mfma_f32_16x16x32_bf16 v[108:111], v[172:175], v[204:207], v[108:111]
	v_mfma_f32_16x16x32_bf16 v[104:107], v[180:183], v[204:207], v[104:107]
	v_mfma_f32_16x16x32_bf16 v[68:71], v[172:175], v[228:231], v[68:71]
	v_mfma_f32_16x16x32_bf16 v[64:67], v[180:183], v[228:231], v[64:67]
	s_barrier
	ds_read_b128 v[184:187], v223 offset:49152
	ds_read_b128 v[188:191], v223 offset:50176
	ds_read_b128 v[192:195], v223 offset:51200
	ds_read_b128 v[196:199], v223 offset:52224
	ds_read_b128 v[200:203], v223 offset:53248
	ds_read_b128 v[204:207], v223 offset:54272
	ds_read_b128 v[224:227], v223 offset:55296
	ds_read_b128 v[228:231], v223 offset:56320
	s_or_b32 s13, s12, 0x4000
	s_mov_b32 m0, s34
	s_nop 0
	buffer_load_dwordx4 v220, s[52:55], s13 offen lds
	s_add_i32 s12, s12, 0x164000
	s_mov_b32 m0, s82
	s_nop 0
	buffer_load_dwordx4 v221, s[52:55], s13 offen lds
	s_nop 0
	s_mov_b32 m0, s85
	s_nop 0
	buffer_load_dwordx4 v220, s[52:55], s12 offen lds
	s_nop 0
	s_mov_b32 m0, s86
	s_nop 0
	buffer_load_dwordx4 v221, s[52:55], s12 offen lds
	s_nop 0
	s_mov_b32 m0, s83
	s_nop 0
	buffer_load_dwordx4 v220, s[20:23], s11 offen lds
	s_nop 0
	s_mov_b32 m0, s84
	s_nop 0
	buffer_load_dwordx4 v221, s[20:23], s11 offen lds
	s_waitcnt vmcnt(8)
	s_waitcnt lgkmcnt(0)
	s_barrier
	s_waitcnt lgkmcnt(7)
	v_mfma_f32_16x16x32_bf16 v[60:63], v[128:131], v[184:187], v[60:63]
	v_mfma_f32_16x16x32_bf16 v[56:59], v[152:155], v[184:187], v[56:59]
	s_waitcnt lgkmcnt(5)
	v_mfma_f32_16x16x32_bf16 v[44:47], v[128:131], v[192:195], v[44:47]
	v_mfma_f32_16x16x32_bf16 v[40:43], v[152:155], v[192:195], v[40:43]
	s_waitcnt lgkmcnt(3)
	v_mfma_f32_16x16x32_bf16 v[28:31], v[128:131], v[200:203], v[28:31]
	v_mfma_f32_16x16x32_bf16 v[24:27], v[152:155], v[200:203], v[24:27]
	s_waitcnt lgkmcnt(1)
	v_mfma_f32_16x16x32_bf16 v[12:15], v[128:131], v[224:227], v[12:15]
	v_mfma_f32_16x16x32_bf16 v[8:11], v[152:155], v[224:227], v[8:11]
	v_mfma_f32_16x16x32_bf16 v[60:63], v[140:143], v[188:191], v[60:63]
	v_mfma_f32_16x16x32_bf16 v[56:59], v[156:159], v[188:191], v[56:59]
	v_mfma_f32_16x16x32_bf16 v[44:47], v[140:143], v[196:199], v[44:47]
	v_mfma_f32_16x16x32_bf16 v[40:43], v[156:159], v[196:199], v[40:43]
	v_mfma_f32_16x16x32_bf16 v[28:31], v[140:143], v[204:207], v[28:31]
	v_mfma_f32_16x16x32_bf16 v[24:27], v[156:159], v[204:207], v[24:27]
	s_waitcnt lgkmcnt(0)
	v_mfma_f32_16x16x32_bf16 v[12:15], v[140:143], v[228:231], v[12:15]
	v_mfma_f32_16x16x32_bf16 v[8:11], v[156:159], v[228:231], v[8:11]
	v_mfma_f32_16x16x32_bf16 v[52:55], v[168:171], v[184:187], v[52:55]
	v_mfma_f32_16x16x32_bf16 v[48:51], v[176:179], v[184:187], v[48:51]
	v_mfma_f32_16x16x32_bf16 v[36:39], v[168:171], v[192:195], v[36:39]
	v_mfma_f32_16x16x32_bf16 v[32:35], v[176:179], v[192:195], v[32:35]
	v_mfma_f32_16x16x32_bf16 v[20:23], v[168:171], v[200:203], v[20:23]
	v_mfma_f32_16x16x32_bf16 v[16:19], v[176:179], v[200:203], v[16:19]
	v_mfma_f32_16x16x32_bf16 v[4:7], v[168:171], v[224:227], v[4:7]
	v_mfma_f32_16x16x32_bf16 v[0:3], v[176:179], v[224:227], v[0:3]
	v_mfma_f32_16x16x32_bf16 v[52:55], v[172:175], v[188:191], v[52:55]
	v_mfma_f32_16x16x32_bf16 v[48:51], v[180:183], v[188:191], v[48:51]
	v_mfma_f32_16x16x32_bf16 v[36:39], v[172:175], v[196:199], v[36:39]
	v_mfma_f32_16x16x32_bf16 v[32:35], v[180:183], v[196:199], v[32:35]
	v_mfma_f32_16x16x32_bf16 v[20:23], v[172:175], v[204:207], v[20:23]
	v_mfma_f32_16x16x32_bf16 v[16:19], v[180:183], v[204:207], v[16:19]
	v_mfma_f32_16x16x32_bf16 v[4:7], v[172:175], v[228:231], v[4:7]
	v_mfma_f32_16x16x32_bf16 v[0:3], v[180:183], v[228:231], v[0:3]
	s_barrier
	s_add_i32 s10, s10, 2
	s_add_i32 s8, s8, 0x8000
	s_add_i32 s9, s9, 0x8000
	.p2align	6
